# v23: v21 + per-tile unit decode: unsigned /8 and %8 of the non-negative unit id (shift, mask, multiply by the positive constant) instead of the signed sequence with sign fix-ups
# speedup vs baseline: 1.0205x; 1.0205x over previous
; template <class Epi, class Ptrs>
; __device__ __forceinline__ void gemm_phase(LAS unsigned char* lds, const int K, const StaticOrder& S, const Ptrs& P, const Epi& E) {
;     ...
;     PG8_STAGE(PG8_SB(0, 0), cB, voffB); PG8_STAGE(PG8_SA(0, 0), cA, voffA); PG8_STAGE(PG8_SB(0, 1), cB + hstep, voffB); PG8_STAGE(PG8_SA(0, 1), cA + hstep, voffA);
;     if (wr == 1) PG8_BAR;
;     PG8_WAIT_V(4); PG8_BAR;
;     PG8_STAGE(PG8_SB(1, 0), cB + kstep, voffB); PG8_STAGE(PG8_SA(1, 0), cA + kstep, voffA); PG8_STAGE(PG8_SB(1, 1), cB + hstep + kstep, voffB);
;     PG8_WAIT_V(6); PG8_BAR;
;     __device__ __forceinline__ void operator()(const f32x4 (&acc)[2][2][4][2], const Unit& u, int ui, int wr, int wc, int fr, int fq) const {
;         const int pn = u.pn;
;         if (pn < 8) {
;             bf16_t* base = (bf16_t*)(ws + WS_U) + (size_t)(u.pm * 256 + wr * 64 + fr) * DM + pn * 128 + wc * 32 + 8 * fq;
; #pragma unroll
;             for (int ai = 0; ai < 2; ++ai)
; #pragma unroll
;                 for (int m = 0; m < 4; ++m) {
;                     const f32x4 g0 = g1_4(acc[ai][0][m][0], acc[ai][1][m][0]), g1 = g1_4(acc[ai][0][m][1], acc[ai][1][m][1]);
;                     *(u32x4*)(base + (size_t)(ai * 128 + m * 16) * DM) = pack8(g0, g1); }
;             return; }
;         if (pn >= 17 && pn < 21) {
;             bf16_t* base = (bf16_t*)(dout + DO_GVT) + (size_t)((pn - 17) * 256 + wr * 64 + fr) * MTOK + u.pm * 256 + wc * 32 + 8 * fq;
;             float* pp = (float*)(ws + WS_PART) + (size_t)(u.pm * 256 + wc * 32 + 8 * fq) * 8 + (pn - 17) * 2 + wr;
; #pragma unroll
;             for (int bj = 0; bj < 2; ++bj) { f32x4 sq0 = {0.f, 0.f, 0.f, 0.f}, sq1 = {0.f, 0.f, 0.f, 0.f};
; #pragma unroll
;                 for (int ai = 0; ai < 2; ++ai)
; #pragma unroll
;                     for (int m = 0; m < 4; ++m) { const f32x4 g0 = gelu4(acc[ai][bj][m][0]), g1 = gelu4(acc[ai][bj][m][1]);
;                         sq0 += g0 * g0; sq1 += g1 * g1;
;                         *(u32x4*)(base + (size_t)(ai * 128 + m * 16) * MTOK + bj * 128) = pack8(g0, g1); }
; #pragma unroll
;                 for (int j = 0; j < 4; ++j) { const float t0 = row16_sum(sq0[j]), t1 = row16_sum(sq1[j]); if (fr == 0) { pp[(size_t)(bj * 128 + j) * 8] = t0; pp[(size_t)(bj * 128 + 4 + j) * 8] = t1; } } }
;             return; }
;         bf16_t* base; size_t ld; int row0, col0, act;
.LBB0_120:
	s_add_u32 s4, s28, 0x35000000
	s_addc_u32 s5, s29, 0
	s_mov_b64 s[58:59], 0x80
	v_writelane_b32 v254, s4, 0
	v_lshl_add_u64 v[6:7], v[6:7], 0, s[58:59]
	s_waitcnt vmcnt(4)
	s_barrier
	v_writelane_b32 v254, s5, 1
	s_add_u32 s4, s28, 0x26000000
	s_addc_u32 s5, s29, 0
	s_add_u32 s42, s28, 0x32000000
	s_addc_u32 s43, s29, 0
	s_add_u32 s44, s28, 0x2000000
	s_addc_u32 s45, s29, 0
	s_add_u32 s48, s26, 0xc000000
	s_addc_u32 s49, s27, 0
	s_add_u32 s54, s28, 0x3e000000
	s_addc_u32 s55, s29, 0
	s_add_u32 s56, s28, 0xe000000
	s_addc_u32 s57, s29, 0
	s_lshl_b32 s1, s1, 5
	s_and_b32 s88, s1, 0x60
	s_add_i32 m0, s67, 0x18000
	v_writelane_b32 v254, s4, 2
	s_ashr_i32 s86, s3, 31
	s_ashr_i32 s87, s2, 31
	s_lshl_b32 s20, s0, 13
	s_lshl_b32 s1, s88, 7
	global_load_lds_dwordx4 v[6:7], off
	v_lshl_add_u64 v[4:5], v[4:5], 0, s[58:59]
	s_add_i32 m0, s67, 0x1a000
	s_add_i32 s89, s67, 0x8000
	s_add_i32 s90, s67, 0xa000
	v_writelane_b32 v254, s5, 3
	global_load_lds_dwordx4 v[4:5], off
	v_lshl_add_u64 v[2:3], v[2:3], 0, s[58:59]
	s_mov_b32 m0, s89
	s_add_u32 s4, s78, 0x40080
	global_load_lds_dwordx4 v[2:3], off
	v_lshl_add_u64 v[0:1], v[0:1], 0, s[58:59]
	s_mov_b32 m0, s90
	s_addc_u32 s5, s79, 0
	global_load_lds_dwordx4 v[0:1], off
	s_add_i32 m0, s67, 0x1c000
	v_lshl_add_u64 v[0:1], s[4:5], 0, v[134:135]
	global_load_lds_dwordx4 v[0:1], off
	v_lshl_add_u64 v[0:1], s[4:5], 0, v[138:139]
	s_add_i32 m0, s67, 0x1e000
	v_lshlrev_b32_e32 v2, 6, v208
	global_load_lds_dwordx4 v[0:1], off
	v_and_b32_e32 v0, 15, v208
	v_lshlrev_b32_e32 v1, 1, v130
	s_movk_i32 s4, 0x3c0
	v_lshlrev_b32_e32 v3, 2, v208
	v_and_or_b32 v2, v2, s4, v1
	v_and_b32_e32 v3, 32, v3
	v_cmp_eq_u32_e64 s[10:11], 0, v0
	v_lshl_or_b32 v129, s0, 6, v0
	v_lshl_or_b32 v0, v0, 6, v1
	v_lshlrev_b32_e32 v1, 8, v208
	v_bitop3_b32 v131, s1, v2, v3 bitop3:0xf6
	v_and_b32_e32 v1, 0x38000, v1
	v_lshlrev_b32_e32 v2, 11, v10
	v_or3_b32 v1, v8, v1, v2
	v_add_u32_e32 v142, v1, v9
	v_lshlrev_b32_e32 v1, 4, v11
	s_waitcnt vmcnt(6)
	v_and_b32_e32 v1, 0x78000, v1
	v_bitop3_b32 v0, v0, s20, v3 bitop3:0xde
	v_or3_b32 v1, v8, v1, v2
	s_add_i32 s91, 0, 0x10000
	s_add_i32 s92, 0, 0x14000
	v_or_b32_e32 v204, s88, v130
	v_mov_b32_e32 v143, v141
	v_add_u32_e32 v144, v1, v9
	v_mov_b32_e32 v145, v141
	v_mov_b64_e32 v[146:147], 0x2100
	v_mov_b64_e32 v[148:149], 0x20ff
	v_add_u32_e32 v205, s91, v131
	v_add_u32_e32 v206, 0, v0
	v_add_u32_e32 v207, s92, v131
	s_mov_b32 s60, 0xbfb8aa3b
	s_lshl_b32 s62, s0, 2
	s_mov_b32 s64, 0x3dd2d3e7
	s_mov_b32 s66, 0xc0135761
	s_mov_b32 s93, 0x600000
	s_mov_b32 s94, 0x900000
	s_mov_b32 s95, 0x1800000
	s_mov_b32 s96, 0x1b00000
	s_mov_b32 s97, 0x1e00000
	s_mov_b32 s98, 0x2100000
	s_mov_b32 s99, 0x40000
	s_mov_b32 s22, 0x48000
	s_mov_b32 s23, 0x50000
	s_nop 0
	s_nop 0
	s_nop 0
	s_nop 0
	s_nop 0
	s_nop 0
	s_nop 0
	s_nop 0
	s_nop 0
	s_nop 0
	s_nop 0
	s_nop 0
	s_nop 0
	s_nop 0
	s_nop 0
	s_nop 0
	s_nop 0
	s_nop 0
	s_nop 0
	s_nop 0
	s_nop 0
	s_nop 0
	s_nop 0
	s_nop 0
	s_nop 0
	s_nop 0
	s_nop 0
	s_nop 0
	s_nop 0
	s_nop 0
	s_nop 0
	s_nop 0
	s_nop 0
	s_nop 0
	s_nop 0
	s_nop 0
	s_nop 0
	s_nop 0
	s_nop 0
	s_nop 0
	s_nop 0
	s_nop 0
	s_nop 0
	s_nop 0
	s_nop 0
	s_nop 0
	s_nop 0
	s_nop 0
	s_nop 0
	s_nop 0
	s_nop 0
	s_nop 0
	s_nop 0
	s_nop 0
	s_nop 0
	s_nop 0
	s_nop 0
	s_nop 0
	s_nop 0
	s_nop 0
	s_nop 0
	s_nop 0
	s_nop 0
	s_mov_b32 s24, 0
	s_cmpk_lt_u32 s61, 0x100
	s_cbranch_scc1 .Lsprio_0
	s_setprio 1

;     __device__ bool next(int i, Unit& u) const {
;         if (rev && i >= rev) return false;
;         const long L = (long)(rev ? rev - 1 - i : i) * G + c; if (L >= nwg) return false;
;         int wgid = (int)L; { const int q = nwg / NXCD, r = nwg % NXCD, xcd = wgid % NXCD, off = wgid / NXCD; wgid = (xcd < r ? xcd * (q + 1) : r * (q + 1) + (xcd - r) * q) + off; }
;         const int nig = WGM * nN, gid = wgid / nig, fm = gid * WGM, gsz = (nM - fm) < WGM ? (nM - fm) : WGM;
;         u.pm = fm + ((wgid % nig) % gsz); u.pn = (wgid % nig) / gsz; return true;
.LBB0_122:
	s_add_i32 s24, s24, 1
	s_mul_i32 s0, s24, s86
	s_mul_hi_u32 s1, s24, s3
	s_add_i32 s1, s1, s0
	s_mul_i32 s0, s24, s3
	s_add_u32 s72, s0, s2
	s_addc_u32 s73, s1, s87
	v_cmp_gt_i64_e64 s[4:5], s[72:73], v[148:149]
	v_cmp_lt_i64_e64 s[0:1], s[72:73], v[146:147]
	s_and_b64 vcc, exec, s[4:5]
	s_cbranch_vccnz .LBB0_124
	s_lshr_b32 s25, s72, 3
	s_and_b32 s20, s72, 7
	s_mulk_i32 s20, 0x420
	s_add_i32 s20, s20, s25
	s_mul_hi_i32 s25, s20, 0x2e8ba2e9
	s_lshr_b32 s63, s25, 31
	s_ashr_i32 s25, s25, 5
	s_add_i32 s25, s25, s63
	s_lshl_b32 s63, s25, 3
	s_mulk_i32 s25, 0xb0
	s_sub_i32 s20, s20, s25
	s_lshr_b32 s68, s20, 3
	s_and_b32 s20, s20, 7
	s_add_i32 s70, s63, s20

; #define PG8_STAGE(bufoff, gbase, voff) do { _Pragma("unroll") for (int _i = 0; _i < 2; ++_i) \
;         __builtin_amdgcn_global_load_lds((const unsigned*)((const char*)(gbase) + (voff)[_i]), (LAS unsigned*)(lds + (bufoff) + ldsw + _i * 8192), 16, 0, 0); } while (0)
; #define PG8_WAIT_V(n) asm volatile("s_waitcnt vmcnt(" #n ")" ::: "memory")
; #define PG8_BAR __builtin_amdgcn_s_barrier()
; template <class Epi, class Ptrs>
; __device__ __forceinline__ void gemm_phase(LAS unsigned char* lds, const int K, const StaticOrder& S, const Ptrs& P, const Epi& E) {
;     ...
;     PG8_STAGE(PG8_SB(0, 0), cB, voffB); PG8_STAGE(PG8_SA(0, 0), cA, voffA); PG8_STAGE(PG8_SB(0, 1), cB + hstep, voffB); PG8_STAGE(PG8_SA(0, 1), cA + hstep, voffA);
;     if (wr == 1) PG8_BAR;
;     PG8_WAIT_V(4); PG8_BAR;
;     PG8_STAGE(PG8_SB(1, 0), cB + kstep, voffB); PG8_STAGE(PG8_SA(1, 0), cA + kstep, voffA); PG8_STAGE(PG8_SB(1, 1), cB + hstep + kstep, voffB);
;     PG8_WAIT_V(6); PG8_BAR;
;     __device__ __forceinline__ void operator()(const f32x4 (&acc)[2][2][4][2], const Unit& u, int ui, int wr, int wc, int fr, int fq) const {
;         const int row0 = u.pm * 256 + wr * 64 + fr, col0 = u.pn * 256 + wc * 32 + 8 * fq;
;         const float* xb0 = (u.pm * 256 < MP) ? xp : xs - (size_t)MP * DM;
.LBB0_346:
	s_add_u32 s14, s28, 0x2000000
	s_addc_u32 s15, s29, 0
	s_add_u32 s16, s28, 0x3e000000
	s_addc_u32 s17, s29, 0
	s_ashr_i32 s58, s3, 31
	s_ashr_i32 s59, s2, 31
	s_add_u32 s60, s38, 0xf8000000
	s_mov_b64 s[18:19], 0x80
	s_addc_u32 s61, s39, -1
	s_and_b32 s62, s1, 3
	s_add_i32 m0, s54, 0x18000
	v_lshl_add_u64 v[6:7], v[6:7], 0, s[18:19]
	s_lshl_b32 s1, s0, 13
	s_lshl_b32 s20, s62, 12
	s_waitcnt vmcnt(4)
	s_barrier
	global_load_lds_dwordx4 v[6:7], off
	v_lshl_add_u64 v[4:5], v[4:5], 0, s[18:19]
	s_add_i32 m0, s54, 0x1a000
	s_add_i32 s63, s54, 0x8000
	s_add_i32 s64, s54, 0xa000
	global_load_lds_dwordx4 v[4:5], off
	v_lshl_add_u64 v[2:3], v[2:3], 0, s[18:19]
	s_mov_b32 m0, s63
	s_add_u32 s4, s42, 0x40080
	global_load_lds_dwordx4 v[2:3], off
	v_lshl_add_u64 v[0:1], v[0:1], 0, s[18:19]
	s_mov_b32 m0, s64
	s_addc_u32 s5, s43, 0
	global_load_lds_dwordx4 v[0:1], off
	s_add_i32 m0, s54, 0x1c000
	v_lshl_add_u64 v[0:1], s[4:5], 0, v[178:179]
	global_load_lds_dwordx4 v[0:1], off
	v_lshl_add_u64 v[0:1], s[4:5], 0, v[182:183]
	s_add_i32 m0, s54, 0x1e000
	v_lshlrev_b32_e32 v4, 6, v208
	global_load_lds_dwordx4 v[0:1], off
	v_bfe_u32 v1, v208, 4, 2
	v_lshlrev_b32_e32 v2, 3, v1
	v_lshlrev_b32_e32 v3, 4, v1
	v_cmp_eq_u32_e64 s[6:7], 0, v1
	v_lshlrev_b32_e32 v1, 8, v208
	v_lshl_or_b32 v206, s62, 5, v2
	v_and_b32_e32 v1, 0x38000, v1
	v_lshlrev_b32_e32 v2, 11, v10
	v_or3_b32 v1, v8, v1, v2
	v_and_b32_e32 v0, 15, v208
	s_movk_i32 s4, 0x3c0
	v_lshlrev_b32_e32 v5, 2, v208
	v_add_u32_e32 v184, v1, v9
	v_lshlrev_b32_e32 v1, 4, v11
	v_and_or_b32 v4, v4, s4, v3
	v_and_b32_e32 v5, 32, v5
	v_lshl_or_b32 v204, s0, 6, v0
	v_lshl_or_b32 v0, v0, 6, v3
	s_waitcnt vmcnt(6)
	v_and_b32_e32 v1, 0x78000, v1
	v_bitop3_b32 v0, v0, s1, v5 bitop3:0xde
	v_bitop3_b32 v205, s20, v4, v5 bitop3:0xf6
	v_or3_b32 v1, v8, v1, v2
	s_add_i32 s66, 0, 0x10000
	s_add_i32 s67, 0, 0x14000
	v_mov_b32_e32 v185, v179
	v_add_u32_e32 v186, v1, v9
	v_mov_b32_e32 v187, v179
	v_mov_b64_e32 v[188:189], 0x600
	v_mov_b64_e32 v[190:191], 0x5ff
	s_movk_i32 s65, 0xc1
	v_add_u32_e32 v207, s66, v205
	v_add_u32_e32 v209, 0, v0
	v_add_u32_e32 v210, s67, v205
	s_nop 0
	s_nop 0
	s_nop 0
	s_nop 0
	s_nop 0
	s_nop 0
	s_nop 0
	s_nop 0
	s_nop 0
	s_nop 0
	s_nop 0
	s_nop 0
	s_nop 0
	s_nop 0
	s_nop 0
	s_nop 0
	s_nop 0
	s_nop 0
	s_nop 0
	s_nop 0
	s_nop 0
	s_nop 0
	s_nop 0
	s_nop 0
	s_nop 0
	s_nop 0
	s_nop 0
	s_nop 0
	s_nop 0
	s_nop 0
	s_nop 0
	s_nop 0
	s_nop 0
	s_nop 0
	s_nop 0
	s_nop 0
	s_nop 0
	s_nop 0
	s_nop 0
	s_nop 0
	s_nop 0
	s_nop 0
	s_nop 0
	s_nop 0
	s_nop 0
	s_nop 0
	s_nop 0
	s_nop 0
	s_nop 0
	s_nop 0
	s_nop 0
	s_nop 0
	s_nop 0
	s_nop 0
	s_nop 0
	s_nop 0
	s_nop 0
	s_nop 0
	s_nop 0
	s_nop 0
	s_nop 0
	s_nop 0
	s_mov_b32 s68, 0
	s_cmpk_lt_u32 s46, 0x100
	s_cbranch_scc1 .Lsprio_1
	s_setprio 1

;     __device__ bool next(int i, Unit& u) const {
;         if (rev && i >= rev) return false;
;         const long L = (long)(rev ? rev - 1 - i : i) * G + c; if (L >= nwg) return false;
;         int wgid = (int)L; { const int q = nwg / NXCD, r = nwg % NXCD, xcd = wgid % NXCD, off = wgid / NXCD; wgid = (xcd < r ? xcd * (q + 1) : r * (q + 1) + (xcd - r) * q) + off; }
;         const int nig = WGM * nN, gid = wgid / nig, fm = gid * WGM, gsz = (nM - fm) < WGM ? (nM - fm) : WGM;
;         u.pm = fm + ((wgid % nig) % gsz); u.pn = (wgid % nig) / gsz; return true;
.LBB0_348:
	s_add_i32 s68, s68, 1
	s_mul_i32 s0, s68, s58
	s_mul_hi_u32 s1, s68, s3
	s_add_i32 s1, s1, s0
	s_mul_i32 s0, s68, s3
	s_add_u32 s24, s0, s2
	s_addc_u32 s25, s1, s59
	v_cmp_gt_i64_e64 s[4:5], s[24:25], v[190:191]
	v_cmp_lt_i64_e64 s[0:1], s[24:25], v[188:189]
	s_and_b64 vcc, exec, s[4:5]
	s_cbranch_vccnz .LBB0_350
	s_lshr_b32 s21, s24, 3
	s_and_b32 s20, s24, 7
	s_mulk_i32 s20, 0xc0
	s_add_i32 s20, s20, s21
	s_ashr_i32 s21, s20, 31
	s_lshr_b32 s21, s21, 27
	s_add_i32 s21, s20, s21
	s_ashr_i32 s22, s21, 5
	s_lshl_b32 s22, s22, 3
	s_andn2_b32 s21, s21, 31
	s_sub_i32 s21, s20, s21
	s_lshr_b32 s20, s21, 3
	s_and_b32 s21, s21, 7
	s_add_i32 s22, s22, s21

; #define PG8_STAGE(bufoff, gbase, voff) do { _Pragma("unroll") for (int _i = 0; _i < 2; ++_i) \
;         __builtin_amdgcn_global_load_lds((const unsigned*)((const char*)(gbase) + (voff)[_i]), (LAS unsigned*)(lds + (bufoff) + ldsw + _i * 8192), 16, 0, 0); } while (0)
; #define PG8_WAIT_V(n) asm volatile("s_waitcnt vmcnt(" #n ")" ::: "memory")
; #define PG8_BAR __builtin_amdgcn_s_barrier()
; template <class Epi, class Ptrs>
; __device__ __forceinline__ void gemm_phase(LAS unsigned char* lds, const int K, const StaticOrder& S, const Ptrs& P, const Epi& E) {
;     ...
;     PG8_STAGE(PG8_SB(0, 0), cB, voffB); PG8_STAGE(PG8_SA(0, 0), cA, voffA); PG8_STAGE(PG8_SB(0, 1), cB + hstep, voffB); PG8_STAGE(PG8_SA(0, 1), cA + hstep, voffA);
;     if (wr == 1) PG8_BAR;
;     PG8_WAIT_V(4); PG8_BAR;
;     PG8_STAGE(PG8_SB(1, 0), cB + kstep, voffB); PG8_STAGE(PG8_SA(1, 0), cA + kstep, voffA); PG8_STAGE(PG8_SB(1, 1), cB + hstep + kstep, voffB);
;     PG8_WAIT_V(6); PG8_BAR;
;     __device__ __forceinline__ void operator()(const f32x4 (&acc)[2][2][4][2], const Unit& u, int ui, int wr, int wc, int fr, int fq) const {
;         const int row0 = u.pm * 256 + wr * 64 + fr, col0 = u.pn * 256 + wc * 32 + 8 * fq;
; #pragma unroll
;         for (int ai = 0; ai < 2; ++ai)
; #pragma unroll
;             for (int m = 0; m < 4; ++m) { bf16_t* rowp = hid + (size_t)(row0 + ai * 128 + m * 16) * DFF + col0;
.LBB0_427:
	s_nop 0
	s_nop 0
	s_nop 0
	s_nop 0
	s_nop 0
	s_nop 0
	s_nop 0
	s_nop 0
	s_nop 0
	s_nop 0
	s_nop 0
	s_nop 0
	s_nop 0
	s_nop 0
	s_nop 0
	s_nop 0
	s_nop 0
	s_nop 0
	s_nop 0
	s_nop 0
	s_nop 0
	s_nop 0
	s_nop 0
	s_nop 0
	s_nop 0
	s_nop 0
	s_nop 0
	s_nop 0
	s_nop 0
	s_nop 0
	s_nop 0
	s_nop 0
	s_nop 0
	s_nop 0
	s_nop 0
	s_nop 0
	s_nop 0
	s_nop 0
	s_nop 0
	s_nop 0
	s_nop 0
	s_nop 0
	s_nop 0
	s_nop 0
	s_nop 0
	s_nop 0
	s_nop 0
	s_nop 0
	s_nop 0
	s_nop 0
	s_nop 0
	s_nop 0
	s_nop 0
	s_nop 0
	s_nop 0
	s_add_u32 s10, s28, 0xe000000
	s_addc_u32 s11, s29, 0
	s_lshl_b32 s4, s4, 5
	s_mov_b64 s[12:13], 0x80
	s_and_b32 s15, s4, 0x60
	s_add_i32 m0, s39, 0x18000
	v_lshl_add_u64 v[6:7], v[6:7], 0, s[12:13]
	s_ashr_i32 s60, s3, 31
	s_lshl_b32 s14, s1, 13
	s_lshl_b32 s16, s15, 7
	s_waitcnt vmcnt(4)
	s_barrier
	global_load_lds_dwordx4 v[6:7], off
	v_lshl_add_u64 v[4:5], v[4:5], 0, s[12:13]
	s_add_i32 m0, s39, 0x1a000
	s_add_i32 s61, s39, 0x8000
	s_add_i32 s62, s39, 0xa000
	global_load_lds_dwordx4 v[4:5], off
	v_lshl_add_u64 v[2:3], v[2:3], 0, s[12:13]
	s_mov_b32 m0, s61
	s_add_u32 s4, s42, 0x40080
	global_load_lds_dwordx4 v[2:3], off
	v_lshl_add_u64 v[0:1], v[0:1], 0, s[12:13]
	s_mov_b32 m0, s62
	s_addc_u32 s5, s43, 0
	global_load_lds_dwordx4 v[0:1], off
	s_add_i32 m0, s39, 0x1c000
	v_lshl_add_u64 v[0:1], s[4:5], 0, v[130:131]
	global_load_lds_dwordx4 v[0:1], off
	v_lshl_add_u64 v[0:1], s[4:5], 0, v[134:135]
	s_add_i32 m0, s39, 0x1e000
	s_sext_i32_i8 s69, s0
	global_load_lds_dwordx4 v[0:1], off
	v_and_b32_e32 v0, 15, v208
	v_lshlrev_b32_e32 v1, 1, v11
	v_lshlrev_b32_e32 v2, 6, v208
	s_movk_i32 s0, 0x3c0
	v_lshlrev_b32_e32 v3, 2, v208
	v_and_or_b32 v2, v2, s0, v1
	v_and_b32_e32 v3, 32, v3
	v_lshl_or_b32 v146, s1, 6, v0
	v_lshl_or_b32 v0, v0, 6, v1
	v_lshlrev_b32_e32 v1, 8, v208
	v_bitop3_b32 v147, s16, v2, v3 bitop3:0xf6
	v_and_b32_e32 v1, 0x38000, v1
	v_lshlrev_b32_e32 v2, 11, v10
	v_or3_b32 v1, v8, v1, v2
	v_add_u32_e32 v136, v1, v9
	v_lshlrev_b32_e32 v1, 4, v12
	s_waitcnt vmcnt(6)
	v_and_b32_e32 v1, 0x78000, v1
	v_bitop3_b32 v0, v0, s14, v3 bitop3:0xde
	v_or3_b32 v1, v8, v1, v2
	s_add_i32 s63, 0, 0x10000
	s_add_i32 s64, 0, 0x14000
	v_or_b32_e32 v148, s15, v11
	v_mov_b32_e32 v137, v131
	v_add_u32_e32 v138, v1, v9
	v_mov_b32_e32 v139, v131
	v_mov_b64_e32 v[140:141], 0x1800
	v_mov_b64_e32 v[142:143], 0x17ff
	v_add_u32_e32 v149, s63, v147
	v_add_u32_e32 v150, 0, v0
	v_add_u32_e32 v151, s64, v147
	s_mov_b64 s[14:15], 0x100000
	s_mov_b32 s65, 0x100000
	s_mov_b64 s[16:17], 0x120000
	s_mov_b32 s66, 0x120000
	s_mov_b64 s[18:19], 0x140000
	s_mov_b32 s67, 0x140000
	s_mov_b64 s[20:21], 0x160000
	s_mov_b32 s68, 0x160000
	s_cmpk_lt_u32 s46, 0x100
	s_cbranch_scc1 .Lsprio_2
	s_setprio 1

;     __device__ bool next(int i, Unit& u) const {
;         if (rev && i >= rev) return false;
;         const long L = (long)(rev ? rev - 1 - i : i) * G + c; if (L >= nwg) return false;
;         int wgid = (int)L; { const int q = nwg / NXCD, r = nwg % NXCD, xcd = wgid % NXCD, off = wgid / NXCD; wgid = (xcd < r ? xcd * (q + 1) : r * (q + 1) + (xcd - r) * q) + off; }
;         const int nig = WGM * nN, gid = wgid / nig, fm = gid * WGM, gsz = (nM - fm) < WGM ? (nM - fm) : WGM;
;         u.pm = fm + ((wgid % nig) % gsz); u.pn = (wgid % nig) / gsz; return true;
.LBB0_428:
	s_add_i32 s59, s59, 1
	s_sub_i32 s74, 23, s59
	s_cmpk_eq_i32 s3, 0x100
	s_cselect_b32 s74, s74, s59
	s_mul_i32 s0, s74, s60
	s_mul_hi_u32 s1, s74, s3
	s_add_i32 s1, s1, s0
	s_mul_i32 s0, s74, s3
	s_add_u32 s36, s0, s2
	s_addc_u32 s37, s1, s54
	v_cmp_gt_i64_e64 s[4:5], s[36:37], v[142:143]
	v_cmp_lt_i64_e64 s[0:1], s[36:37], v[140:141]
	s_and_b64 vcc, exec, s[4:5]
	s_cbranch_vccnz .LBB0_430
	s_lshr_b32 s23, s36, 3
	s_and_b32 s22, s36, 7
	s_mulk_i32 s22, 0x300
	s_add_i32 s22, s22, s23
	s_ashr_i32 s23, s22, 31
	s_lshr_b32 s23, s23, 25
	s_add_i32 s23, s22, s23
	s_ashr_i32 s24, s23, 7
	s_lshl_b32 s24, s24, 3
	s_and_b32 s23, s23, 0xffffff80
	s_sub_i32 s23, s22, s23
	s_lshr_b32 s22, s23, 3
	s_and_b32 s23, s23, 7
	s_add_i32 s24, s24, s23

; #define PG8_STAGE(bufoff, gbase, voff) do { _Pragma("unroll") for (int _i = 0; _i < 2; ++_i) \
;         __builtin_amdgcn_global_load_lds((const unsigned*)((const char*)(gbase) + (voff)[_i]), (LAS unsigned*)(lds + (bufoff) + ldsw + _i * 8192), 16, 0, 0); } while (0)
; #define PG8_WAIT_V(n) asm volatile("s_waitcnt vmcnt(" #n ")" ::: "memory")
; #define PG8_BAR __builtin_amdgcn_s_barrier()
; template <class Epi, class Ptrs>
; __device__ __forceinline__ void gemm_phase(LAS unsigned char* lds, const int K, const StaticOrder& S, const Ptrs& P, const Epi& E) {
;     ...
;     PG8_STAGE(PG8_SB(0, 0), cB, voffB); PG8_STAGE(PG8_SA(0, 0), cA, voffA); PG8_STAGE(PG8_SB(0, 1), cB + hstep, voffB); PG8_STAGE(PG8_SA(0, 1), cA + hstep, voffA);
;     if (wr == 1) PG8_BAR;
;     PG8_WAIT_V(4); PG8_BAR;
;     PG8_STAGE(PG8_SB(1, 0), cB + kstep, voffB); PG8_STAGE(PG8_SA(1, 0), cA + kstep, voffA); PG8_STAGE(PG8_SB(1, 1), cB + hstep + kstep, voffB);
;     PG8_WAIT_V(6); PG8_BAR;
;     __device__ __forceinline__ void operator()(const f32x4 (&acc)[2][2][4][2], const Unit& u, int ui, int wr, int wc, int fr, int fq) const {
;         const int rl0 = wr * 64 + fr, col0 = u.pn * 256 + wc * 32 + 8 * fq;
;         u32x4 xv[2][4][2];
; #pragma unroll
;         for (int ai = 0; ai < 2; ++ai)
; #pragma unroll
;             for (int m = 0; m < 4; ++m)
; #pragma unroll
;                 for (int bj = 0; bj < 2; ++bj) xv[ai][m][bj] = *(const u32x4*)(xb + (size_t)(u.pm * 256 + rl0 + ai * 128 + m * 16) * DM + col0 + bj * 128);
; #pragma unroll
;         for (int ai = 0; ai < 2; ++ai)
; #pragma unroll
;             for (int m = 0; m < 4; ++m) { const int rl = rl0 + ai * 128 + m * 16; float* rowp = out + (size_t)(u.pm * 256 + rl) * DM + col0;
;                 const float r2 = tab[ui * 256 + rl];
.LBB0_516:
	s_lshl_b32 s1, s1, 5
	s_and_b32 s1, s1, 0x60
	s_lshl_b32 s10, s0, 13
	s_lshl_b32 s11, s1, 7
	s_add_u32 s6, s28, 0x2000000
	s_mov_b64 s[8:9], 0x80
	s_addc_u32 s7, s29, 0
	s_add_i32 m0, s17, 0x18000
	v_lshl_add_u64 v[6:7], v[6:7], 0, s[8:9]
	s_waitcnt vmcnt(4)
	s_barrier
	global_load_lds_dwordx4 v[6:7], off
	v_lshl_add_u64 v[4:5], v[4:5], 0, s[8:9]
	s_add_i32 m0, s17, 0x1a000
	s_add_i32 s28, s17, 0x8000
	s_add_i32 s29, s17, 0xa000
	global_load_lds_dwordx4 v[4:5], off
	v_lshl_add_u64 v[2:3], v[2:3], 0, s[8:9]
	s_mov_b32 m0, s28
	s_add_u32 s4, s22, 0x100080
	global_load_lds_dwordx4 v[2:3], off
	v_lshl_add_u64 v[0:1], v[0:1], 0, s[8:9]
	s_mov_b32 m0, s29
	s_addc_u32 s5, s23, 0
	global_load_lds_dwordx4 v[0:1], off
	s_add_i32 m0, s17, 0x1c000
	v_lshl_add_u64 v[0:1], s[4:5], 0, v[162:163]
	global_load_lds_dwordx4 v[0:1], off
	v_lshl_add_u64 v[0:1], s[4:5], 0, v[166:167]
	s_add_i32 m0, s17, 0x1e000
	v_lshlrev_b32_e32 v2, 6, v208
	global_load_lds_dwordx4 v[0:1], off
	v_and_b32_e32 v0, 15, v208
	v_lshlrev_b32_e32 v1, 1, v11
	s_movk_i32 s4, 0x3c0
	v_lshl_or_b32 v186, s0, 6, v0
	v_and_or_b32 v2, v2, s4, v1
	v_lshlrev_b32_e32 v3, 2, v208
	v_lshl_or_b32 v0, v0, 6, v1
	v_lshlrev_b32_e32 v1, 2, v186
	s_add_i32 s0, 0, 0x20000
	v_and_b32_e32 v3, 32, v3
	v_and_b32_e32 v4, 32, v1
	v_add_u32_e32 v192, s0, v1
	v_lshlrev_b32_e32 v1, 10, v208
	v_bitop3_b32 v187, s11, v2, v3 bitop3:0xf6
	v_and_b32_e32 v1, 0xe0000, v1
	v_lshlrev_b32_e32 v2, 13, v10
	v_or3_b32 v1, v8, v1, v2
	v_add_u32_e32 v168, v1, v9
	v_lshlrev_b32_e32 v1, 6, v12
	s_waitcnt vmcnt(6)
	v_and_b32_e32 v1, 0x1e0000, v1
	v_bitop3_b32 v0, v0, s10, v4 bitop3:0xde
	v_or3_b32 v1, v8, v1, v2
	s_add_i32 s42, 0, 0x10000
	s_add_i32 s43, 0, 0x14000
	v_or_b32_e32 v188, 16, v186
	v_or_b32_e32 v189, 32, v186
	v_or_b32_e32 v190, 48, v186
	v_or_b32_e32 v191, s1, v11
	v_mov_b32_e32 v169, v163
	v_add_u32_e32 v170, v1, v9
	v_mov_b32_e32 v171, v163
	v_mov_b64_e32 v[172:173], 0x600
	v_mov_b64_e32 v[174:175], 0x5ff
	v_add_u32_e32 v193, s42, v187
	v_add_u32_e32 v194, 0, v0
	s_nop 0
	s_nop 0
	s_nop 0
	s_nop 0
	s_nop 0
	s_nop 0
	s_nop 0
	s_nop 0
	s_nop 0
	s_nop 0
	s_nop 0
	s_nop 0
	s_nop 0
	s_nop 0
	s_nop 0
	s_nop 0
	s_nop 0
	s_nop 0
	s_nop 0
	s_nop 0
	s_nop 0
	s_nop 0
	s_nop 0
	s_nop 0
	s_nop 0
	s_nop 0
	s_nop 0
	s_nop 0
	s_nop 0
	s_nop 0
	s_nop 0
	s_nop 0
	s_nop 0
	s_nop 0
	s_nop 0
	s_nop 0
	s_nop 0
	s_nop 0
	s_nop 0
	s_nop 0
	s_nop 0
	s_nop 0
	s_nop 0
	s_nop 0
	s_nop 0
	s_nop 0
	s_nop 0
	s_nop 0
	s_nop 0
	s_nop 0
	s_nop 0
	s_nop 0
	s_nop 0
	s_nop 0
	s_nop 0
	s_nop 0
	s_nop 0
	s_nop 0
	s_nop 0
	s_nop 0
	s_nop 0
	s_nop 0
	v_add_u32_e32 v195, s43, v187
	s_cmpk_lt_u32 s33, 0x100
	s_cbranch_scc1 .Lsprio_3
	s_setprio 1

;     __device__ bool next(int i, Unit& u) const {
;         if (rev && i >= rev) return false;
;         const long L = (long)(rev ? rev - 1 - i : i) * G + c; if (L >= nwg) return false;
;         int wgid = (int)L; { const int q = nwg / NXCD, r = nwg % NXCD, xcd = wgid % NXCD, off = wgid / NXCD; wgid = (xcd < r ? xcd * (q + 1) : r * (q + 1) + (xcd - r) * q) + off; }
;         const int nig = WGM * nN, gid = wgid / nig, fm = gid * WGM, gsz = (nM - fm) < WGM ? (nM - fm) : WGM;
;         u.pm = fm + ((wgid % nig) % gsz); u.pn = (wgid % nig) / gsz; return true;
.LBB0_517:
	s_add_i32 s44, s45, 1
	s_mul_i32 s0, s44, s30
	s_mul_hi_u32 s1, s44, s3
	s_add_i32 s1, s1, s0
	s_mul_i32 s0, s44, s3
	s_add_u32 s14, s0, s2
	s_addc_u32 s15, s1, s31
	v_cmp_gt_i64_e64 s[0:1], s[14:15], v[174:175]
	v_cmp_lt_i64_e64 s[4:5], s[14:15], v[172:173]
	s_and_b64 vcc, exec, s[0:1]
	s_cbranch_vccnz .LBB0_519
	s_lshr_b32 s11, s14, 3
	s_and_b32 s10, s14, 7
	s_mulk_i32 s10, 0xc0
	s_add_i32 s10, s10, s11
	s_ashr_i32 s11, s10, 31
	s_lshr_b32 s11, s11, 27
	s_add_i32 s11, s10, s11
	s_ashr_i32 s12, s11, 5
	s_lshl_b32 s12, s12, 3
	s_andn2_b32 s11, s11, 31
	s_sub_i32 s11, s10, s11
	s_lshr_b32 s10, s11, 3
	s_and_b32 s11, s11, 7
	s_add_i32 s12, s12, s11
